# attention sel/window step loop rewritten by hand: software-pipelined QK(j) with softmax+PV(j-1), in-place accumulators
# speedup vs baseline: 1.0331x; 1.0331x over previous
; #define LAS __attribute__((address_space(3)))
; #define RING_ISSUE(SI) do { int kbi = kb0 + (SI) * 32; if (kbi > kb_last) kbi = kb_last; const int slot = (SI) % 3; \
;           const h16* srcp = wave < 4 ? kbase + (size_t)kbi * LDH + k_src_off : vT + (size_t)(kbi >> 5) * 2048 + v_src_off; \
;           __builtin_amdgcn_global_load_lds((const unsigned*)srcp, (LAS unsigned*)(ring + slot * 8192 + stage_dst), 16, 0, 0); } while (0)
; DI void attn_phase(const Params& p, const int layer, const int wid_s) {
;     ...
;       const int kb_last = qblk * 64 + 32;
;       const int kmax_w = (t0 + 15) & ~31;
; #pragma unroll 1
;       for (int br = 1; br <= 2; ++br) {
;         const h16* kbase = hb + (br == 1 ? C_KS : C_KW) + g * 64;
;         const h16* vT = (const h16*)(p.ws + (br == 1 ? OFF_VST : OFF_VWT)) + (size_t)bg * 64 * SEQ;
;         int kb0 = 0, lo_w = 0;
;         if (br == 2) { kb0 = qblk * 64 - 512; if (kb0 < 0) kb0 = 0; lo_w = t0 - 511; if (lo_w < 0) lo_w = 0; lo_w &= ~31; }
;         const int nsteps = (kb_last - kb0) / 32 + 1;
;         f32x4 O[2][4]; float l[2];
; #pragma unroll
;         for (int hp = 0; hp < 2; ++hp) { l[hp] = 0.f;
; #pragma unroll
;           for (int dt = 0; dt < 4; ++dt) O[hp][dt] = (f32x4){0.f, 0.f, 0.f, 0.f}; }
;     ...
;         asm volatile("s_waitcnt vmcnt(0)" ::: "memory");
;         __syncthreads();
;         RING_ISSUE(0); RING_ISSUE(1);
; #pragma unroll 1
;         for (int si = 0; si < nsteps; ++si) {
;           asm volatile("s_waitcnt vmcnt(1) lgkmcnt(0)" ::: "memory");
;           __builtin_amdgcn_s_barrier();
;           asm volatile("" ::: "memory");
;           RING_ISSUE(si + 2);
;           const int kb = kb0 + si * 32;
;           if (kb > kmax_w || kb < lo_w) continue;
;           if (br == 1 && kb + 31 + 128 <= t0 && __ballot((selmask >> (kb >> 6)) & 1u) == 0ull) continue;
;           LAS unsigned char* slotp = ring + (si % 3) * 8192;
.LBB0_345:
	s_add_i32 m0, s13, 0x1b880
	s_sub_i32 s13, s14, s12
	global_load_lds_dwordx4 v[2:3], off
	s_xor_b64 s[6:7], s[4:5], -1
	s_ashr_i32 s13, s13, 5
	v_mov_b32_e32 v3, 0
	s_cmp_lt_i32 s13, 0
	v_mov_b32_e32 v2, v3
	v_mov_b32_e32 v67, v3
	v_mov_b32_e32 v66, v3
	v_mov_b32_e32 v65, v3
	v_mov_b32_e32 v64, v3
	v_mov_b32_e32 v59, v3
	v_mov_b32_e32 v58, v3
	v_mov_b32_e32 v57, v3
	v_mov_b32_e32 v56, v3
	v_mov_b32_e32 v55, v3
	v_mov_b32_e32 v54, v3
	v_mov_b32_e32 v53, v3
	v_mov_b32_e32 v52, v3
	v_mov_b32_e32 v51, v3
	v_mov_b32_e32 v50, v3
	v_mov_b32_e32 v49, v3
	v_mov_b32_e32 v48, v3
	v_mov_b32_e32 v47, v3
	v_mov_b32_e32 v46, v3
	v_mov_b32_e32 v45, v3
	v_mov_b32_e32 v44, v3
	v_mov_b32_e32 v43, v3
	v_mov_b32_e32 v42, v3
	v_mov_b32_e32 v41, v3
	v_mov_b32_e32 v40, v3
	v_mov_b32_e32 v39, v3
	v_mov_b32_e32 v38, v3
	v_mov_b32_e32 v37, v3
	v_mov_b32_e32 v36, v3
	v_mov_b32_e32 v35, v3
	v_mov_b32_e32 v34, v3
	v_mov_b32_e32 v33, v3
	v_mov_b32_e32 v32, v3
	s_cbranch_scc1 .LBB0_368
	v_mov_b32_e32 v2, v1
	v_mov_b32_e32 v3, v1
	s_and_b64 s[40:41], s[4:5], exec
	v_lshl_add_u64 v[6:7], s[10:11], 0, v[0:1]
	v_mov_b32_e32 v0, v1
	v_mov_b32_e32 v32, 0
	v_mov_b64_e32 v[62:63], v[2:3]
	s_mov_b32 s39, 0
	s_cselect_b32 s40, s21, 0
	v_lshl_add_u64 v[152:153], v[144:145], 1, s[8:9]
	s_add_i32 s41, s13, 1
	s_add_i32 s42, s12, 0x1f1
	v_subrev_u32_e32 v151, s12, v195
	s_mov_b32 s43, 2
	s_mov_b32 s44, 0
	v_mov_b64_e32 v[60:61], v[0:1]
	v_mov_b32_e32 v33, v32
	v_mov_b32_e32 v34, v32
	v_mov_b32_e32 v35, v32
	v_mov_b32_e32 v48, v32
	v_mov_b32_e32 v49, v32
	v_mov_b32_e32 v50, v32
	v_mov_b32_e32 v51, v32
	v_mov_b32_e32 v36, v32
	v_mov_b32_e32 v37, v32
	v_mov_b32_e32 v38, v32
	v_mov_b32_e32 v39, v32
	v_mov_b32_e32 v52, v32
	v_mov_b32_e32 v53, v32
	v_mov_b32_e32 v54, v32
	v_mov_b32_e32 v55, v32
	v_mov_b32_e32 v40, v32
	v_mov_b32_e32 v41, v32
	v_mov_b32_e32 v42, v32
	v_mov_b32_e32 v43, v32
	v_mov_b32_e32 v56, v32
	v_mov_b32_e32 v57, v32
	v_mov_b32_e32 v58, v32
	v_mov_b32_e32 v59, v32
	v_mov_b32_e32 v44, v32
	v_mov_b32_e32 v45, v32
	v_mov_b32_e32 v46, v32
	v_mov_b32_e32 v47, v32
	v_mov_b32_e32 v2, v32
	v_mov_b32_e32 v3, v32
	v_mov_b32_e32 v64, v32
	v_mov_b32_e32 v65, v32
	v_mov_b32_e32 v66, v32
	v_mov_b32_e32 v67, v32
	s_movk_i32 s42, 0x1400
	s_and_b64 vcc, exec, s[30:31]
	s_cselect_b32 s42, 0x80, s42
	v_cndmask_b32_e32 v240, v152, v6, vcc
	v_cndmask_b32_e32 v241, v153, v7, vcc
	s_mov_b32 s45, s12
	s_mov_b32 s39, 0x19880
	s_mov_b32 s43, s24
	s_mov_b32 s44, 0
	s_mov_b32 s13, -1
	v_mov_b32_e32 v214, 0
	v_mov_b32_e32 v215, 0
	v_mov_b32_e32 v216, 0
	v_mov_b32_e32 v217, 0
	v_mov_b32_e32 v218, 0
	v_mov_b32_e32 v219, 0
	v_mov_b32_e32 v220, 0
	v_mov_b32_e32 v221, 0
	s_and_b64 vcc, exec, s[4:5]
	s_cbranch_vccnz .Lat_prewin
	v_mov_b32_e32 v242, v193
	v_mov_b32_e32 v243, v194
	v_mov_b32_e32 v244, v5
	v_bfrev_b32_e32 v247, 1
	s_branch .LBB0_349
.Lat_prewin:
	v_mov_b32_e32 v242, v24
	v_mov_b32_e32 v243, v28
	v_mov_b32_e32 v244, -1
	v_mov_b32_e32 v247, 0x200
	s_branch .LBB0_349
.LBB0_349:
	s_waitcnt vmcnt(1) lgkmcnt(0)
	s_barrier
	s_cmp_gt_i32 s45, s15
	s_cbranch_scc1 .Lat_skip
	s_cmp_lt_i32 s45, s40
	s_cbranch_scc1 .Lat_skip
	s_add_i32 s10, s45, 0x9f
	s_cmp_gt_i32 s10, s51
	s_cselect_b32 s11, 2, 0
	s_add_i32 s10, s45, 0x1f1
	s_cmp_le_i32 s10, s51
	s_cselect_b32 s10, 2, 0
	s_and_b32 s10, s10, s4
	s_or_b32 s11, s11, s10
	s_cmp_lg_u32 s11, 0
	s_cbranch_scc1 .Lat_comp
	s_and_b64 vcc, exec, s[4:5]
	s_cbranch_vccnz .Lat_comp
	s_lshr_b32 s10, s45, 6
	v_bfe_u32 v0, v5, s10, 1
	v_cmp_ne_u32_e32 vcc, 0, v0
	s_cmp_lg_u64 vcc, 0
	s_cbranch_scc0 .Lat_skip
.Lat_comp:
	v_add_u32_e32 v0, s39, v185
	v_add_u32_e32 v64, s39, v184
	ds_read_b128 v[96:99], v0
	ds_read_b128 v[92:95], v64
	ds_read_b128 v[88:91], v0 offset:2048
	ds_read_b128 v[84:87], v64 offset:2048
	s_add_i32 s8, s45, 64
	s_min_i32 s8, s8, s14
	s_mul_i32 s8, s8, s42
	s_mov_b32 s9, 0
	v_lshl_add_u64 v[238:239], v[240:241], 0, s[8:9]
	s_mov_b32 m0, s43
	s_add_i32 s43, s43, 0x2000
	global_load_lds_dwordx4 v[238:239], off
	s_cmp_gt_u32 s43, s24
	s_cselect_b32 s8, 0x6000, 0
	s_sub_i32 s43, s43, s8
	s_lshr_b32 s10, s45, 6
	s_cmp_eq_u32 s10, s13
	s_cbranch_scc1 .Lat_cok_c
	s_mov_b32 s13, s10
	v_bfe_u32 v65, v244, s10, 1
	v_cmp_ne_u32_e32 vcc, 0, v65
	s_nop 1
	v_cndmask_b32_e32 v128, v4, v242, vcc
	v_cndmask_b32_e32 v132, v4, v243, vcc
	v_cndmask_b32_e32 v129, v4, v242, vcc
	v_cndmask_b32_e32 v133, v4, v243, vcc
	v_cndmask_b32_e32 v130, v4, v242, vcc
	v_cndmask_b32_e32 v134, v4, v243, vcc
	v_cndmask_b32_e32 v131, v4, v242, vcc
	v_cndmask_b32_e32 v135, v4, v243, vcc
; #define MFMA16(a, b, c) __builtin_amdgcn_mfma_f32_16x16x32_f16((a), (b), (c), 0, 0, 0)
; template <bool SEL, bool GEN>
; DI void attn_step(const KF& kv, const int kb, const int t, const int lane, const bool selbit,
;                   const LAS float* tabh, const half8 (&q)[2][2], f32x4 (&O)[2][4], const float (&nR)[2], float (&l)[2]) {
;     ...
;   for (int hp = 0; hp < 2; ++hp) {
;     float nm = nR[hp];
;     if (SEL) nm = selbit ? nm : MASKV;
;     const f32x4 c0 = {nm, nm, nm, nm};
; #pragma unroll
;     for (int kt = 0; kt < 2; ++kt) {
;       s[hp][kt] = MFMA16(kv.k[kt][0], q[hp][0], c0);
;       s[hp][kt] = MFMA16(kv.k[kt][1], q[hp][1], s[hp][kt]);
;     }
;   }
;   if (GEN) {
;     const int d0 = t - kb - fq * 4;
; #pragma unroll
;     for (int kt = 0; kt < 2; ++kt)
; #pragma unroll
;       for (int j = 0; j < 4; ++j) {
;         const int dist = d0 - (kt * 16 + j);
;         const bool bad = SEL ? (dist < 0) : ((unsigned)dist >= 512u);
;         const int ix = bad ? 130 : (dist > 128 ? 128 : dist);
; #pragma unroll
;         for (int hp = 0; hp < 2; ++hp) s[hp][kt][j] += tabh[hp * 132 + ix];
;       }
;   }
;   half8 pf[2];
; #pragma unroll
;   for (int hp = 0; hp < 2; ++hp) {
;     f32x4 p0, p1;
; #pragma unroll
;     for (int j = 0; j < 4; ++j) { p0[j] = __builtin_amdgcn_exp2f(s[hp][0][j]); p1[j] = __builtin_amdgcn_exp2f(s[hp][1][j]); }
;     l[hp] += ((p0[0] + p0[1]) + (p0[2] + p0[3])) + ((p1[0] + p1[1]) + (p1[2] + p1[3]));
;     pf[hp] = pack8(p0, p1);
;   }
; #pragma unroll
;   for (int dt = 0; dt < 4; ++dt)
; #pragma unroll
;     for (int hp = 0; hp < 2; ++hp) O[hp][dt] = MFMA16(kv.v[dt], pf[hp], O[hp][dt]);
.Lat_cok_c:
	s_bitcmp1_b32 s44, 0
	s_cbranch_scc0 .Lat_pathb
	s_bitcmp1_b32 s44, 1
	s_cbranch_scc0 .Lat_nogen_a
	v_add_u32_e32 v116, 19, v246
	v_add_u32_e32 v117, 18, v246
	v_cmp_gt_u32_e64 s[8:9], v247, v116
	v_cmp_gt_u32_e64 vcc, v247, v117
	v_min_u32_e32 v116, 0x80, v116
	v_min_u32_e32 v117, 0x80, v117
	v_cndmask_b32_e64 v116, v161, v116, s[8:9]
	v_cndmask_b32_e64 v117, v161, v117, vcc
	v_lshl_add_u32 v116, v116, 2, s38
	v_lshl_add_u32 v117, v117, 2, s38
	ds_read2_b32 v[222:223], v116 offset1:132
	ds_read2_b32 v[224:225], v117 offset1:132
	v_add_u32_e32 v116, 17, v246
	v_add_u32_e32 v117, 16, v246
	v_cmp_gt_u32_e64 s[8:9], v247, v116
	v_cmp_gt_u32_e64 vcc, v247, v117
	v_min_u32_e32 v116, 0x80, v116
	v_min_u32_e32 v117, 0x80, v117
	v_cndmask_b32_e64 v116, v161, v116, s[8:9]
	v_cndmask_b32_e64 v117, v161, v117, vcc
	v_lshl_add_u32 v116, v116, 2, s38
	v_lshl_add_u32 v117, v117, 2, s38
	ds_read2_b32 v[226:227], v116 offset1:132
	ds_read2_b32 v[228:229], v117 offset1:132
	v_add_u32_e32 v116, 3, v246
	v_add_u32_e32 v117, 2, v246
	v_cmp_gt_u32_e64 s[8:9], v247, v116
	v_cmp_gt_u32_e64 vcc, v247, v117
	v_min_u32_e32 v116, 0x80, v116
	v_min_u32_e32 v117, 0x80, v117
	v_cndmask_b32_e64 v116, v161, v116, s[8:9]
	v_cndmask_b32_e64 v117, v161, v117, vcc
	v_lshl_add_u32 v116, v116, 2, s38
	v_lshl_add_u32 v117, v117, 2, s38
	ds_read2_b32 v[230:231], v116 offset1:132
	ds_read2_b32 v[232:233], v117 offset1:132
	v_add_u32_e32 v116, 1, v246
	v_add_u32_e32 v117, 0, v246
	v_cmp_gt_u32_e64 s[8:9], v247, v116
	v_cmp_gt_u32_e64 vcc, v247, v117
	v_min_u32_e32 v116, 0x80, v116
	v_min_u32_e32 v117, 0x80, v117
	v_cndmask_b32_e64 v116, v161, v116, s[8:9]
	v_cndmask_b32_e64 v117, v161, v117, vcc
	v_lshl_add_u32 v116, v116, 2, s38
	v_lshl_add_u32 v117, v117, 2, s38
	ds_read2_b32 v[234:235], v116 offset1:132
	ds_read2_b32 v[236:237], v117 offset1:132
	s_waitcnt lgkmcnt(0)
	v_add_f32_e32 v100, v100, v222
	v_add_f32_e32 v108, v108, v223
	v_add_f32_e32 v101, v101, v224
	v_add_f32_e32 v109, v109, v225
	v_add_f32_e32 v102, v102, v226
	v_add_f32_e32 v110, v110, v227
	v_add_f32_e32 v103, v103, v228
	v_add_f32_e32 v111, v111, v229
	v_add_f32_e32 v104, v104, v230
	v_add_f32_e32 v112, v112, v231
	v_add_f32_e32 v105, v105, v232
	v_add_f32_e32 v113, v113, v233
	v_add_f32_e32 v106, v106, v234
	v_add_f32_e32 v114, v114, v235
	v_add_f32_e32 v107, v107, v236
	v_add_f32_e32 v115, v115, v237
.Lat_nogen_a:
	v_exp_f32_e32 v198, v100
	v_exp_f32_e32 v199, v101
	v_exp_f32_e32 v200, v102
	v_exp_f32_e32 v201, v103
	v_exp_f32_e32 v202, v104
	v_exp_f32_e32 v203, v105
	v_exp_f32_e32 v204, v106
	v_exp_f32_e32 v205, v107
	s_waitcnt lgkmcnt(0)
	v_mfma_f32_16x16x32_f16 v[100:103], v[96:99], v[8:11], v[128:131]
	v_exp_f32_e32 v206, v108
	v_exp_f32_e32 v207, v109
	v_mfma_f32_16x16x32_f16 v[104:107], v[88:91], v[8:11], v[128:131]
	v_exp_f32_e32 v208, v110
	v_exp_f32_e32 v209, v111
	v_mfma_f32_16x16x32_f16 v[108:111], v[96:99], v[16:19], v[132:135]
	v_exp_f32_e32 v210, v112
	v_exp_f32_e32 v211, v113
	v_mfma_f32_16x16x32_f16 v[100:103], v[92:95], v[12:15], v[100:103]
	v_exp_f32_e32 v212, v114
	v_exp_f32_e32 v213, v115
	v_mfma_f32_16x16x32_f16 v[112:115], v[88:91], v[16:19], v[132:135]
	v_cvt_pkrtz_f16_f32 v120, v198, v199
	v_cvt_pkrtz_f16_f32 v121, v200, v201
	v_mfma_f32_16x16x32_f16 v[104:107], v[84:87], v[12:15], v[104:107]
	v_cvt_pkrtz_f16_f32 v122, v202, v203
	v_cvt_pkrtz_f16_f32 v123, v204, v205
	v_mfma_f32_16x16x32_f16 v[108:111], v[92:95], v[20:23], v[108:111]
	v_cvt_pkrtz_f16_f32 v124, v206, v207
	v_cvt_pkrtz_f16_f32 v125, v208, v209
	v_mfma_f32_16x16x32_f16 v[112:115], v[84:87], v[20:23], v[112:115]
	v_cvt_pkrtz_f16_f32 v126, v210, v211
	v_cvt_pkrtz_f16_f32 v127, v212, v213
	v_subrev_u32_e32 v246, s45, v195
	s_or_b32 s44, s11, 1
	v_mfma_f32_16x16x32_f16 v[60:63], v[80:83], v[120:123], v[60:63]
	v_add_f32_e32 v214, v214, v198
	v_add_f32_e32 v215, v215, v199
	v_mfma_f32_16x16x32_f16 v[56:59], v[76:79], v[120:123], v[56:59]
	v_add_f32_e32 v216, v216, v200
	v_add_f32_e32 v217, v217, v201
	v_mfma_f32_16x16x32_f16 v[52:55], v[72:75], v[120:123], v[52:55]
	v_add_f32_e32 v214, v214, v202
	v_add_f32_e32 v215, v215, v203
	v_mfma_f32_16x16x32_f16 v[48:51], v[68:71], v[120:123], v[48:51]
	v_add_f32_e32 v216, v216, v204
	v_add_f32_e32 v217, v217, v205
	v_mfma_f32_16x16x32_f16 v[44:47], v[80:83], v[124:127], v[44:47]
	v_add_f32_e32 v218, v218, v206
	v_add_f32_e32 v219, v219, v207
	v_mfma_f32_16x16x32_f16 v[40:43], v[76:79], v[124:127], v[40:43]
	v_add_f32_e32 v220, v220, v208
	v_add_f32_e32 v221, v221, v209
	v_mfma_f32_16x16x32_f16 v[36:39], v[72:75], v[124:127], v[36:39]
	v_add_f32_e32 v218, v218, v210
	v_add_f32_e32 v219, v219, v211
	v_mfma_f32_16x16x32_f16 v[32:35], v[68:71], v[124:127], v[32:35]
	v_add_f32_e32 v220, v220, v212
	v_add_f32_e32 v221, v221, v213
	v_add_u32_e32 v65, s39, v183
	ds_read_b128 v[80:83], v65 offset:4096
	ds_read_b128 v[76:79], v65 offset:5120
	ds_read_b128 v[72:75], v65 offset:6144
	ds_read_b128 v[68:71], v65 offset:7168
	s_branch .Lat_next
.Lat_pathb:
	s_waitcnt lgkmcnt(0)
	v_mfma_f32_16x16x32_f16 v[100:103], v[96:99], v[8:11], v[128:131]
	v_mfma_f32_16x16x32_f16 v[104:107], v[88:91], v[8:11], v[128:131]
	v_mfma_f32_16x16x32_f16 v[108:111], v[96:99], v[16:19], v[132:135]
	v_mfma_f32_16x16x32_f16 v[112:115], v[88:91], v[16:19], v[132:135]
	v_mfma_f32_16x16x32_f16 v[100:103], v[92:95], v[12:15], v[100:103]
	v_mfma_f32_16x16x32_f16 v[104:107], v[84:87], v[12:15], v[104:107]
	v_mfma_f32_16x16x32_f16 v[108:111], v[92:95], v[20:23], v[108:111]
	v_mfma_f32_16x16x32_f16 v[112:115], v[84:87], v[20:23], v[112:115]
	v_subrev_u32_e32 v246, s45, v195
	s_or_b32 s44, s11, 1
	v_add_u32_e32 v65, s39, v183
	ds_read_b128 v[80:83], v65 offset:4096
	ds_read_b128 v[76:79], v65 offset:5120
	ds_read_b128 v[72:75], v65 offset:6144
	ds_read_b128 v[68:71], v65 offset:7168
	s_branch .Lat_next
; #define MFMA16(a, b, c) __builtin_amdgcn_mfma_f32_16x16x32_f16((a), (b), (c), 0, 0, 0)
; #define RING_ISSUE(SI) do { int kbi = kb0 + (SI) * 32; if (kbi > kb_last) kbi = kb_last; const int slot = (SI) % 3; \
;           const h16* srcp = wave < 4 ? kbase + (size_t)kbi * LDH + k_src_off : vT + (size_t)(kbi >> 5) * 2048 + v_src_off; \
;           __builtin_amdgcn_global_load_lds((const unsigned*)srcp, (LAS unsigned*)(ring + slot * 8192 + stage_dst), 16, 0, 0); } while (0)
; template <bool SEL, bool GEN>
; DI void attn_step(const KF& kv, const int kb, const int t, const int lane, const bool selbit,
;                   const LAS float* tabh, const half8 (&q)[2][2], f32x4 (&O)[2][4], const float (&nR)[2], float (&l)[2]) {
;     ...
;   if (GEN) {
;     const int d0 = t - kb - fq * 4;
; #pragma unroll
;     for (int kt = 0; kt < 2; ++kt)
; #pragma unroll
;       for (int j = 0; j < 4; ++j) {
;         const int dist = d0 - (kt * 16 + j);
;         const bool bad = SEL ? (dist < 0) : ((unsigned)dist >= 512u);
;         const int ix = bad ? 130 : (dist > 128 ? 128 : dist);
; #pragma unroll
;         for (int hp = 0; hp < 2; ++hp) s[hp][kt][j] += tabh[hp * 132 + ix];
;       }
;   }
;   half8 pf[2];
; #pragma unroll
;   for (int hp = 0; hp < 2; ++hp) {
;     f32x4 p0, p1;
; #pragma unroll
;     for (int j = 0; j < 4; ++j) { p0[j] = __builtin_amdgcn_exp2f(s[hp][0][j]); p1[j] = __builtin_amdgcn_exp2f(s[hp][1][j]); }
;     l[hp] += ((p0[0] + p0[1]) + (p0[2] + p0[3])) + ((p1[0] + p1[1]) + (p1[2] + p1[3]));
;     pf[hp] = pack8(p0, p1);
;   }
; #pragma unroll
;   for (int dt = 0; dt < 4; ++dt)
; #pragma unroll
;     for (int hp = 0; hp < 2; ++hp) O[hp][dt] = MFMA16(kv.v[dt], pf[hp], O[hp][dt]);
; DI void attn_phase(const Params& p, const int layer, const int wid_s) {
;     ...
;           RING_ISSUE(si + 2);
;           const int kb = kb0 + si * 32;
;           if (kb > kmax_w || kb < lo_w) continue;
.Lat_skip:
	s_add_i32 s8, s45, 64
	s_min_i32 s8, s8, s14
	s_mul_i32 s8, s8, s42
	s_mov_b32 s9, 0
	v_lshl_add_u64 v[238:239], v[240:241], 0, s[8:9]
	s_mov_b32 m0, s43
	s_add_i32 s43, s43, 0x2000
	global_load_lds_dwordx4 v[238:239], off
	s_cmp_gt_u32 s43, s24
	s_cselect_b32 s8, 0x6000, 0
	s_sub_i32 s43, s43, s8
	s_bitcmp1_b32 s44, 0
	s_cbranch_scc0 .Lat_next
	s_bitcmp1_b32 s44, 1
	s_cbranch_scc0 .Lat_nogen_s
	v_add_u32_e32 v116, 19, v246
	v_add_u32_e32 v117, 18, v246
	v_cmp_gt_u32_e64 s[8:9], v247, v116
	v_cmp_gt_u32_e64 vcc, v247, v117
	v_min_u32_e32 v116, 0x80, v116
	v_min_u32_e32 v117, 0x80, v117
	v_cndmask_b32_e64 v116, v161, v116, s[8:9]
	v_cndmask_b32_e64 v117, v161, v117, vcc
	v_lshl_add_u32 v116, v116, 2, s38
	v_lshl_add_u32 v117, v117, 2, s38
	ds_read2_b32 v[222:223], v116 offset1:132
	ds_read2_b32 v[224:225], v117 offset1:132
	v_add_u32_e32 v116, 17, v246
	v_add_u32_e32 v117, 16, v246
	v_cmp_gt_u32_e64 s[8:9], v247, v116
	v_cmp_gt_u32_e64 vcc, v247, v117
	v_min_u32_e32 v116, 0x80, v116
	v_min_u32_e32 v117, 0x80, v117
	v_cndmask_b32_e64 v116, v161, v116, s[8:9]
	v_cndmask_b32_e64 v117, v161, v117, vcc
	v_lshl_add_u32 v116, v116, 2, s38
	v_lshl_add_u32 v117, v117, 2, s38
	ds_read2_b32 v[226:227], v116 offset1:132
	ds_read2_b32 v[228:229], v117 offset1:132
	v_add_u32_e32 v116, 3, v246
	v_add_u32_e32 v117, 2, v246
	v_cmp_gt_u32_e64 s[8:9], v247, v116
	v_cmp_gt_u32_e64 vcc, v247, v117
	v_min_u32_e32 v116, 0x80, v116
	v_min_u32_e32 v117, 0x80, v117
	v_cndmask_b32_e64 v116, v161, v116, s[8:9]
	v_cndmask_b32_e64 v117, v161, v117, vcc
	v_lshl_add_u32 v116, v116, 2, s38
	v_lshl_add_u32 v117, v117, 2, s38
	ds_read2_b32 v[230:231], v116 offset1:132
	ds_read2_b32 v[232:233], v117 offset1:132
	v_add_u32_e32 v116, 1, v246
	v_add_u32_e32 v117, 0, v246
	v_cmp_gt_u32_e64 s[8:9], v247, v116
	v_cmp_gt_u32_e64 vcc, v247, v117
	v_min_u32_e32 v116, 0x80, v116
	v_min_u32_e32 v117, 0x80, v117
	v_cndmask_b32_e64 v116, v161, v116, s[8:9]
	v_cndmask_b32_e64 v117, v161, v117, vcc
	v_lshl_add_u32 v116, v116, 2, s38
	v_lshl_add_u32 v117, v117, 2, s38
	ds_read2_b32 v[234:235], v116 offset1:132
	ds_read2_b32 v[236:237], v117 offset1:132
	s_waitcnt lgkmcnt(0)
	v_add_f32_e32 v100, v100, v222
	v_add_f32_e32 v108, v108, v223
	v_add_f32_e32 v101, v101, v224
	v_add_f32_e32 v109, v109, v225
	v_add_f32_e32 v102, v102, v226
	v_add_f32_e32 v110, v110, v227
	v_add_f32_e32 v103, v103, v228
	v_add_f32_e32 v111, v111, v229
	v_add_f32_e32 v104, v104, v230
	v_add_f32_e32 v112, v112, v231
	v_add_f32_e32 v105, v105, v232
	v_add_f32_e32 v113, v113, v233
	v_add_f32_e32 v106, v106, v234
	v_add_f32_e32 v114, v114, v235
	v_add_f32_e32 v107, v107, v236
	v_add_f32_e32 v115, v115, v237
.Lat_nogen_s:
	v_exp_f32_e32 v198, v100
	v_exp_f32_e32 v199, v101
	v_exp_f32_e32 v200, v102
	v_exp_f32_e32 v201, v103
	v_exp_f32_e32 v202, v104
	v_exp_f32_e32 v203, v105
	v_exp_f32_e32 v204, v106
	v_exp_f32_e32 v205, v107
	v_exp_f32_e32 v206, v108
	v_exp_f32_e32 v207, v109
	v_exp_f32_e32 v208, v110
	v_exp_f32_e32 v209, v111
	v_exp_f32_e32 v210, v112
	v_exp_f32_e32 v211, v113
	v_exp_f32_e32 v212, v114
	v_exp_f32_e32 v213, v115
	v_cvt_pkrtz_f16_f32 v120, v198, v199
	v_cvt_pkrtz_f16_f32 v121, v200, v201
	v_cvt_pkrtz_f16_f32 v122, v202, v203
	v_cvt_pkrtz_f16_f32 v123, v204, v205
	v_cvt_pkrtz_f16_f32 v124, v206, v207
	v_cvt_pkrtz_f16_f32 v125, v208, v209
	v_cvt_pkrtz_f16_f32 v126, v210, v211
	v_cvt_pkrtz_f16_f32 v127, v212, v213
	s_nop 1
	v_mfma_f32_16x16x32_f16 v[60:63], v[80:83], v[120:123], v[60:63]
	v_add_f32_e32 v214, v214, v198
	v_add_f32_e32 v215, v215, v199
	v_mfma_f32_16x16x32_f16 v[56:59], v[76:79], v[120:123], v[56:59]
	v_add_f32_e32 v216, v216, v200
	v_add_f32_e32 v217, v217, v201
	v_mfma_f32_16x16x32_f16 v[52:55], v[72:75], v[120:123], v[52:55]
	v_add_f32_e32 v214, v214, v202
	v_add_f32_e32 v215, v215, v203
	v_mfma_f32_16x16x32_f16 v[48:51], v[68:71], v[120:123], v[48:51]
	v_add_f32_e32 v216, v216, v204
	v_add_f32_e32 v217, v217, v205
	v_mfma_f32_16x16x32_f16 v[44:47], v[80:83], v[124:127], v[44:47]
	v_add_f32_e32 v218, v218, v206
	v_add_f32_e32 v219, v219, v207
	v_mfma_f32_16x16x32_f16 v[40:43], v[76:79], v[124:127], v[40:43]
	v_add_f32_e32 v220, v220, v208
	v_add_f32_e32 v221, v221, v209
	v_mfma_f32_16x16x32_f16 v[36:39], v[72:75], v[124:127], v[36:39]
	v_add_f32_e32 v218, v218, v210
	v_add_f32_e32 v219, v219, v211
	v_mfma_f32_16x16x32_f16 v[32:35], v[68:71], v[124:127], v[32:35]
	v_add_f32_e32 v220, v220, v212
	v_add_f32_e32 v221, v221, v213
	s_mov_b32 s44, 0
; #define MFMA16(a, b, c) __builtin_amdgcn_mfma_f32_16x16x32_f16((a), (b), (c), 0, 0, 0)
; #define RING_ISSUE(SI) do { int kbi = kb0 + (SI) * 32; if (kbi > kb_last) kbi = kb_last; const int slot = (SI) % 3; \
;           const h16* srcp = wave < 4 ? kbase + (size_t)kbi * LDH + k_src_off : vT + (size_t)(kbi >> 5) * 2048 + v_src_off; \
;           __builtin_amdgcn_global_load_lds((const unsigned*)srcp, (LAS unsigned*)(ring + slot * 8192 + stage_dst), 16, 0, 0); } while (0)
; template <bool SEL, bool GEN>
; DI void attn_step(const KF& kv, const int kb, const int t, const int lane, const bool selbit,
;                   const LAS float* tabh, const half8 (&q)[2][2], f32x4 (&O)[2][4], const float (&nR)[2], float (&l)[2]) {
;     ...
;   if (GEN) {
;     const int d0 = t - kb - fq * 4;
; #pragma unroll
;     for (int kt = 0; kt < 2; ++kt)
; #pragma unroll
;       for (int j = 0; j < 4; ++j) {
;         const int dist = d0 - (kt * 16 + j);
;         const bool bad = SEL ? (dist < 0) : ((unsigned)dist >= 512u);
;         const int ix = bad ? 130 : (dist > 128 ? 128 : dist);
; #pragma unroll
;         for (int hp = 0; hp < 2; ++hp) s[hp][kt][j] += tabh[hp * 132 + ix];
;       }
;   }
;   half8 pf[2];
; #pragma unroll
;   for (int hp = 0; hp < 2; ++hp) {
;     f32x4 p0, p1;
; #pragma unroll
;     for (int j = 0; j < 4; ++j) { p0[j] = __builtin_amdgcn_exp2f(s[hp][0][j]); p1[j] = __builtin_amdgcn_exp2f(s[hp][1][j]); }
;     l[hp] += ((p0[0] + p0[1]) + (p0[2] + p0[3])) + ((p1[0] + p1[1]) + (p1[2] + p1[3]));
;     pf[hp] = pack8(p0, p1);
;   }
; #pragma unroll
;   for (int dt = 0; dt < 4; ++dt)
; #pragma unroll
;     for (int hp = 0; hp < 2; ++hp) O[hp][dt] = MFMA16(kv.v[dt], pf[hp], O[hp][dt]);
; DI void attn_phase(const Params& p, const int layer, const int wid_s) {
;     ...
;         for (int si = 0; si < nsteps; ++si) {
;           asm volatile("s_waitcnt vmcnt(1) lgkmcnt(0)" ::: "memory");
;           __builtin_amdgcn_s_barrier();
;           asm volatile("" ::: "memory");
;           RING_ISSUE(si + 2);
.Lat_next:
	s_add_i32 s39, s39, 0x2000
	s_cmp_lt_u32 s39, 0x1f880
	s_cselect_b32 s39, s39, 0x19880
	s_add_i32 s45, s45, 32
	s_add_i32 s41, s41, -1
	s_cmp_lg_u32 s41, 0
	s_cbranch_scc1 .LBB0_349
	s_bitcmp1_b32 s44, 0
	s_cbranch_scc0 .Lat_done
	s_bitcmp1_b32 s44, 1
	s_cbranch_scc0 .Lat_nogen_x
	v_add_u32_e32 v116, 19, v246
	v_add_u32_e32 v117, 18, v246
	v_cmp_gt_u32_e64 s[8:9], v247, v116
	v_cmp_gt_u32_e64 vcc, v247, v117
	v_min_u32_e32 v116, 0x80, v116
	v_min_u32_e32 v117, 0x80, v117
	v_cndmask_b32_e64 v116, v161, v116, s[8:9]
	v_cndmask_b32_e64 v117, v161, v117, vcc
	v_lshl_add_u32 v116, v116, 2, s38
	v_lshl_add_u32 v117, v117, 2, s38
	ds_read2_b32 v[222:223], v116 offset1:132
	ds_read2_b32 v[224:225], v117 offset1:132
	v_add_u32_e32 v116, 17, v246
	v_add_u32_e32 v117, 16, v246
	v_cmp_gt_u32_e64 s[8:9], v247, v116
	v_cmp_gt_u32_e64 vcc, v247, v117
	v_min_u32_e32 v116, 0x80, v116
	v_min_u32_e32 v117, 0x80, v117
	v_cndmask_b32_e64 v116, v161, v116, s[8:9]
	v_cndmask_b32_e64 v117, v161, v117, vcc
	v_lshl_add_u32 v116, v116, 2, s38
	v_lshl_add_u32 v117, v117, 2, s38
	ds_read2_b32 v[226:227], v116 offset1:132
	ds_read2_b32 v[228:229], v117 offset1:132
	v_add_u32_e32 v116, 3, v246
	v_add_u32_e32 v117, 2, v246
	v_cmp_gt_u32_e64 s[8:9], v247, v116
	v_cmp_gt_u32_e64 vcc, v247, v117
	v_min_u32_e32 v116, 0x80, v116
	v_min_u32_e32 v117, 0x80, v117
	v_cndmask_b32_e64 v116, v161, v116, s[8:9]
	v_cndmask_b32_e64 v117, v161, v117, vcc
	v_lshl_add_u32 v116, v116, 2, s38
	v_lshl_add_u32 v117, v117, 2, s38
	ds_read2_b32 v[230:231], v116 offset1:132
	ds_read2_b32 v[232:233], v117 offset1:132
	v_add_u32_e32 v116, 1, v246
	v_add_u32_e32 v117, 0, v246
	v_cmp_gt_u32_e64 s[8:9], v247, v116
	v_cmp_gt_u32_e64 vcc, v247, v117
	v_min_u32_e32 v116, 0x80, v116
	v_min_u32_e32 v117, 0x80, v117
	v_cndmask_b32_e64 v116, v161, v116, s[8:9]
	v_cndmask_b32_e64 v117, v161, v117, vcc
	v_lshl_add_u32 v116, v116, 2, s38
	v_lshl_add_u32 v117, v117, 2, s38
	ds_read2_b32 v[234:235], v116 offset1:132
	ds_read2_b32 v[236:237], v117 offset1:132
	s_waitcnt lgkmcnt(0)
	v_add_f32_e32 v100, v100, v222
	v_add_f32_e32 v108, v108, v223
	v_add_f32_e32 v101, v101, v224
	v_add_f32_e32 v109, v109, v225
	v_add_f32_e32 v102, v102, v226
	v_add_f32_e32 v110, v110, v227
	v_add_f32_e32 v103, v103, v228
	v_add_f32_e32 v111, v111, v229
	v_add_f32_e32 v104, v104, v230
	v_add_f32_e32 v112, v112, v231
	v_add_f32_e32 v105, v105, v232
	v_add_f32_e32 v113, v113, v233
	v_add_f32_e32 v106, v106, v234
	v_add_f32_e32 v114, v114, v235
	v_add_f32_e32 v107, v107, v236
	v_add_f32_e32 v115, v115, v237
.Lat_nogen_x:
	v_exp_f32_e32 v198, v100
	v_exp_f32_e32 v199, v101
	v_exp_f32_e32 v200, v102
	v_exp_f32_e32 v201, v103
	v_exp_f32_e32 v202, v104
	v_exp_f32_e32 v203, v105
	v_exp_f32_e32 v204, v106
	v_exp_f32_e32 v205, v107
	v_exp_f32_e32 v206, v108
	v_exp_f32_e32 v207, v109
	v_exp_f32_e32 v208, v110
	v_exp_f32_e32 v209, v111
	v_exp_f32_e32 v210, v112
	v_exp_f32_e32 v211, v113
	v_exp_f32_e32 v212, v114
	v_exp_f32_e32 v213, v115
	v_cvt_pkrtz_f16_f32 v120, v198, v199
	v_cvt_pkrtz_f16_f32 v121, v200, v201
	v_cvt_pkrtz_f16_f32 v122, v202, v203
	v_cvt_pkrtz_f16_f32 v123, v204, v205
	v_cvt_pkrtz_f16_f32 v124, v206, v207
	v_cvt_pkrtz_f16_f32 v125, v208, v209
	v_cvt_pkrtz_f16_f32 v126, v210, v211
	v_cvt_pkrtz_f16_f32 v127, v212, v213
	s_nop 1
	v_mfma_f32_16x16x32_f16 v[60:63], v[80:83], v[120:123], v[60:63]
	v_add_f32_e32 v214, v214, v198
	v_add_f32_e32 v215, v215, v199
	v_mfma_f32_16x16x32_f16 v[56:59], v[76:79], v[120:123], v[56:59]
	v_add_f32_e32 v216, v216, v200
	v_add_f32_e32 v217, v217, v201
	v_mfma_f32_16x16x32_f16 v[52:55], v[72:75], v[120:123], v[52:55]
	v_add_f32_e32 v214, v214, v202
	v_add_f32_e32 v215, v215, v203
	v_mfma_f32_16x16x32_f16 v[48:51], v[68:71], v[120:123], v[48:51]
	v_add_f32_e32 v216, v216, v204
	v_add_f32_e32 v217, v217, v205
	v_mfma_f32_16x16x32_f16 v[44:47], v[80:83], v[124:127], v[44:47]
	v_add_f32_e32 v218, v218, v206
	v_add_f32_e32 v219, v219, v207
	v_mfma_f32_16x16x32_f16 v[40:43], v[76:79], v[124:127], v[40:43]
	v_add_f32_e32 v220, v220, v208
	v_add_f32_e32 v221, v221, v209
	v_mfma_f32_16x16x32_f16 v[36:39], v[72:75], v[124:127], v[36:39]
	v_add_f32_e32 v218, v218, v210
	v_add_f32_e32 v219, v219, v211
	v_mfma_f32_16x16x32_f16 v[32:35], v[68:71], v[124:127], v[32:35]
	v_add_f32_e32 v220, v220, v212
	v_add_f32_e32 v221, v221, v213
.Lat_done:
	s_nop 7
	s_nop 7
	v_add_f32_e32 v214, v214, v215
	v_add_f32_e32 v216, v216, v217
	v_add_f32_e32 v218, v218, v219
	v_add_f32_e32 v220, v220, v221
	v_add_f32_e32 v2, v214, v216
	v_add_f32_e32 v3, v218, v220
	v_mov_b32_e32 v64, v60
	v_mov_b32_e32 v65, v61
	v_mov_b32_e32 v66, v62
	v_mov_b32_e32 v67, v63
	s_branch .LBB0_368
